# v38 plus V fragment reads issued one per PV MFMA (4 in flight) in the pipelined attention fast path
# speedup vs baseline: 1.0197x; 1.0013x over previous
; template <bool NOSHIFT> __device__ __forceinline__ void diff_attn_unit(LAS unsigned char* lds, bf16_t* proj, const bf16_t* VT, int b, int h, int qb, const AttnConsts ac, const float* gsub, const int tid, bf16_t* obuf, int opitch, int ocol) {
;     ...
;     ATT_ISSUE(0); ATT_ISSUE(1);
;     ATT_WAITBAR(4);
;     for (int t = 0; t < NT; ++t) {
;         const int bo = (t & 3) * 16384, sl_cur = bo, sl_prev = ((t - 1) & 3) * 16384;
;         if (t + 2 < NT) ATT_ISSUE(t + 2);
;         const int kv0 = 64 * t;
;         if (c == 1 && t >= 1 && kv0 - 64 <= qmax) ATT_PV(sl_prev);
;         if (kv0 <= qmax) {
;             f32x16 p[2];
;             bf16x8 kf[2][4];
; #pragma unroll
;             for (int mt = 0; mt < 2; ++mt)
; #pragma unroll
;                 for (int ks = 0; ks < 4; ++ks) kf[mt][ks] = *(const LAS bf16x8*)(lds + bo + koff[mt][ks]);
;             if constexpr (!NOSHIFT) {
; #pragma unroll
;                 for (int mt = 0; mt < 2; ++mt)
; #pragma unroll
;                     for (int r = 0; r < 16; ++r) p[mt][r] = -ac.Mfix;
;             }
;             ATT_SB;
;             __builtin_amdgcn_s_setprio(1);
; #pragma unroll
;             for (int ks = 0; ks < 4; ++ks)
; #pragma unroll
;                 for (int mt = 0; mt < 2; ++mt) {
;                     if (NOSHIFT && ks == 0) { const f32x16 z = {0.f, 0.f, 0.f, 0.f, 0.f, 0.f, 0.f, 0.f, 0.f, 0.f, 0.f, 0.f, 0.f, 0.f, 0.f, 0.f}; p[mt] = __builtin_amdgcn_mfma_f32_32x32x16_bf16(kf[mt][ks], qf[ks], z, 0, 0, 0); }
;                     else p[mt] = __builtin_amdgcn_mfma_f32_32x32x16_bf16(kf[mt][ks], qf[ks], p[mt], 0, 0, 0);
;                 }
;             __builtin_amdgcn_s_setprio(0);
;             ATT_SB;
;             const bool diag = (t >= 2 * qb);
;             if (diag) {
;                 const int qrel = qrow - kv0 - 8 * hi;
; #pragma unroll
;                 for (int mt = 0; mt < 2; ++mt)
; #pragma unroll
;                     for (int r = 0; r < 16; ++r) { float v = __builtin_amdgcn_exp2f(p[mt][r]); if (32 * mt + 16 * (r >> 3) + (r & 7) > qrel) v = 0.f; p[mt][r] = v; l += v; }
;             } else {
; #pragma unroll
;                 for (int mt = 0; mt < 2; ++mt)
; #pragma unroll
;                     for (int r = 0; r < 16; ++r) { const float v = __builtin_amdgcn_exp2f(p[mt][r]); p[mt][r] = v; l += v; }
;             }
;             asm volatile("" ::: "memory");
; #pragma unroll
.Lfp_go:
	s_addk_i32 s14, 0x4000
	s_and_b32 s15, s14, 0xc000
	v_add_u32_e32 v7, s15, v179
	v_add_u32_e32 v96, s15, v183
	v_add_u32_e32 v97, s15, v186
	v_add_u32_e32 v98, s15, v187
	ds_read_b128 v[8:11], v7
	ds_read_b128 v[12:15], v7 offset:8192
	ds_read_b128 v[128:131], v96
	ds_read_b128 v[132:135], v96 offset:8192
	ds_read_b128 v[136:139], v97
	ds_read_b128 v[140:143], v97 offset:8192
	ds_read_b128 v[144:147], v98
	ds_read_b128 v[148:151], v98 offset:8192
	s_add_i32 s80, s14, 0x8000
	s_and_b32 s80, s80, 0xc000
	v_lshl_add_u64 v[152:153], s[96:97], 0, v[4:5]
	s_mov_b64 s[16:17], 0x9e82000
	v_lshl_add_u64 v[154:155], v[152:153], 0, s[16:17]
	s_mov_b64 s[16:17], 0x9f42000
	v_lshl_add_u64 v[152:153], v[152:153], 0, s[16:17]
	v_lshl_add_u64 v[156:157], s[96:97], 0, v[2:3]
	s_mov_b64 s[16:17], 0x21a00180
	v_lshl_add_u64 v[158:159], v[156:157], 0, s[16:17]
	s_mov_b64 s[16:17], 0x21c00180
	v_lshl_add_u64 v[156:157], v[156:157], 0, s[16:17]
	s_add_i32 s81, s80, s59
	s_add_i32 s16, s80, s54
	s_setprio 1
	s_waitcnt lgkmcnt(7)
	v_mfma_f32_32x32x16_bf16 v[96:111], v[8:11], v[160:163], 0
	s_waitcnt lgkmcnt(6)
	v_mfma_f32_32x32x16_bf16 v[112:127], v[12:15], v[160:163], 0
	s_waitcnt lgkmcnt(5)
	v_mfma_f32_32x32x16_bf16 v[96:111], v[128:131], v[164:167], v[96:111]
	s_waitcnt lgkmcnt(4)
	v_mfma_f32_32x32x16_bf16 v[112:127], v[132:135], v[164:167], v[112:127]
	s_waitcnt lgkmcnt(3)
	v_mfma_f32_32x32x16_bf16 v[96:111], v[136:139], v[168:171], v[96:111]
	s_waitcnt lgkmcnt(2)
	v_mfma_f32_32x32x16_bf16 v[112:127], v[140:143], v[168:171], v[112:127]
	s_waitcnt lgkmcnt(1)
	v_mfma_f32_32x32x16_bf16 v[96:111], v[144:147], v[172:175], v[96:111]
	s_waitcnt lgkmcnt(0)
	v_mfma_f32_32x32x16_bf16 v[112:127], v[148:151], v[172:175], v[112:127]
	s_add_i32 s80, s14, 0xc000
	s_and_b32 s80, s80, 0xc000
	v_add_u32_e32 v144, s80, v193
	v_add_u32_e32 v145, s80, v204
	v_add_u32_e32 v146, s80, v205
	v_add_u32_e32 v147, s80, v206
	ds_read_b128 v[128:131], v144
	ds_read_b128 v[132:135], v144 offset:4096
	ds_read_b128 v[136:139], v144 offset:8192
	ds_read_b128 v[140:143], v144 offset:12288
	s_nop 1
	v_exp_f32_e32 v96, v96
	v_exp_f32_e32 v97, v97
	v_exp_f32_e32 v98, v98
	v_exp_f32_e32 v99, v99
	v_exp_f32_e32 v100, v100
	v_exp_f32_e32 v101, v101
	v_exp_f32_e32 v102, v102
	v_exp_f32_e32 v103, v103
	ds_read_b128 v[224:227], v145
	s_waitcnt lgkmcnt(4)
	v_mfma_f32_32x32x16_bf16 v[80:95], v[128:131], v[208:211], v[80:95]
	v_exp_f32_e32 v104, v104
	v_exp_f32_e32 v105, v105
	v_add_f32_e32 v7, v207, v96
	v_add_f32_e32 v7, v97, v7
	ds_read_b128 v[228:231], v145 offset:4096
	s_waitcnt lgkmcnt(4)
	v_mfma_f32_32x32x16_bf16 v[64:79], v[132:135], v[208:211], v[64:79]
	v_exp_f32_e32 v106, v106
	v_exp_f32_e32 v107, v107
	v_add_f32_e32 v7, v98, v7
	v_add_f32_e32 v7, v99, v7
	ds_read_b128 v[232:235], v145 offset:8192
	s_waitcnt lgkmcnt(4)
	v_mfma_f32_32x32x16_bf16 v[48:63], v[136:139], v[208:211], v[48:63]
	v_exp_f32_e32 v108, v108
	v_exp_f32_e32 v109, v109
	v_add_f32_e32 v7, v100, v7
	v_add_f32_e32 v7, v101, v7
	ds_read_b128 v[236:239], v145 offset:12288
	s_waitcnt lgkmcnt(4)
	v_mfma_f32_32x32x16_bf16 v[32:47], v[140:143], v[208:211], v[32:47]
	v_exp_f32_e32 v110, v110
	v_exp_f32_e32 v111, v111
	v_add_f32_e32 v7, v102, v7
	v_add_f32_e32 v7, v103, v7
	s_mov_b32 m0, s81
	s_nop 0
	global_load_lds_dwordx4 v[154:155], off
	ds_read_b128 v[128:131], v146
	s_waitcnt lgkmcnt(4)
	v_mfma_f32_32x32x16_bf16 v[80:95], v[224:227], v[212:215], v[80:95]
	v_cvt_pk_bf16_f32 v208, v96, v97
	v_cvt_pk_bf16_f32 v209, v98, v99
	v_exp_f32_e32 v112, v112
	v_exp_f32_e32 v113, v113
	v_add_f32_e32 v7, v104, v7
	ds_read_b128 v[132:135], v146 offset:4096
	s_waitcnt lgkmcnt(4)
	v_mfma_f32_32x32x16_bf16 v[64:79], v[228:231], v[212:215], v[64:79]
	v_cvt_pk_bf16_f32 v210, v100, v101
	v_cvt_pk_bf16_f32 v211, v102, v103
	v_exp_f32_e32 v114, v114
	v_exp_f32_e32 v115, v115
	v_add_f32_e32 v7, v105, v7
	ds_read_b128 v[136:139], v146 offset:8192
	s_waitcnt lgkmcnt(4)
	v_mfma_f32_32x32x16_bf16 v[48:63], v[232:235], v[212:215], v[48:63]
	v_exp_f32_e32 v116, v116
	v_exp_f32_e32 v117, v117
	v_add_f32_e32 v7, v106, v7
	v_add_f32_e32 v7, v107, v7
	v_add_f32_e32 v7, v108, v7
	ds_read_b128 v[140:143], v146 offset:12288
	s_waitcnt lgkmcnt(4)
	v_mfma_f32_32x32x16_bf16 v[32:47], v[236:239], v[212:215], v[32:47]
	v_exp_f32_e32 v118, v118
	v_exp_f32_e32 v119, v119
	v_add_f32_e32 v7, v109, v7
	v_add_f32_e32 v7, v110, v7
	v_add_f32_e32 v7, v111, v7
	s_add_i32 m0, s81, 0x2000
	s_nop 0
	global_load_lds_dwordx4 v[152:153], off
	ds_read_b128 v[224:227], v147
	s_waitcnt lgkmcnt(4)
	v_mfma_f32_32x32x16_bf16 v[80:95], v[128:131], v[216:219], v[80:95]
	v_cvt_pk_bf16_f32 v212, v104, v105
	v_cvt_pk_bf16_f32 v213, v106, v107
	v_exp_f32_e32 v120, v120
	v_exp_f32_e32 v121, v121
	v_add_f32_e32 v7, v112, v7
	ds_read_b128 v[228:231], v147 offset:4096
	s_waitcnt lgkmcnt(4)
	v_mfma_f32_32x32x16_bf16 v[64:79], v[132:135], v[216:219], v[64:79]
	v_cvt_pk_bf16_f32 v214, v108, v109
	v_cvt_pk_bf16_f32 v215, v110, v111
	v_exp_f32_e32 v122, v122
	v_exp_f32_e32 v123, v123
	v_add_f32_e32 v7, v113, v7
	ds_read_b128 v[232:235], v147 offset:8192
	s_waitcnt lgkmcnt(4)
	v_mfma_f32_32x32x16_bf16 v[48:63], v[136:139], v[216:219], v[48:63]
	v_exp_f32_e32 v124, v124
	v_exp_f32_e32 v125, v125
	v_add_f32_e32 v7, v114, v7
	v_add_f32_e32 v7, v115, v7
	v_add_f32_e32 v7, v116, v7
	ds_read_b128 v[236:239], v147 offset:12288
	s_waitcnt lgkmcnt(4)
	v_mfma_f32_32x32x16_bf16 v[32:47], v[140:143], v[216:219], v[32:47]
	v_exp_f32_e32 v126, v126
	v_exp_f32_e32 v127, v127
	v_add_f32_e32 v7, v117, v7
	v_add_f32_e32 v7, v118, v7
	v_add_f32_e32 v7, v119, v7
	s_mov_b32 m0, s16
	s_nop 0
	global_load_lds_dwordx4 v[158:159], off
	s_waitcnt lgkmcnt(3)
	v_mfma_f32_32x32x16_bf16 v[80:95], v[224:227], v[220:223], v[80:95]
	v_cvt_pk_bf16_f32 v216, v112, v113
	v_cvt_pk_bf16_f32 v217, v114, v115
	v_cvt_pk_bf16_f32 v218, v116, v117
	v_cvt_pk_bf16_f32 v219, v118, v119
	s_waitcnt lgkmcnt(2)
	v_mfma_f32_32x32x16_bf16 v[64:79], v[228:231], v[220:223], v[64:79]
	v_add_f32_e32 v7, v120, v7
	v_add_f32_e32 v7, v121, v7
	v_add_f32_e32 v7, v122, v7
	v_add_f32_e32 v7, v123, v7
	s_waitcnt lgkmcnt(1)
	v_mfma_f32_32x32x16_bf16 v[48:63], v[232:235], v[220:223], v[48:63]
	v_add_f32_e32 v7, v124, v7
	v_add_f32_e32 v7, v125, v7
	v_add_f32_e32 v7, v126, v7
	v_add_f32_e32 v7, v127, v7
	s_waitcnt lgkmcnt(0)
	v_mfma_f32_32x32x16_bf16 v[32:47], v[236:239], v[220:223], v[32:47]
	s_add_i32 m0, s16, 0x2000
	s_nop 0
	global_load_lds_dwordx4 v[156:157], off
	v_cvt_pk_bf16_f32 v220, v120, v121
	v_cvt_pk_bf16_f32 v221, v122, v123
	v_cvt_pk_bf16_f32 v222, v124, v125
	v_cvt_pk_bf16_f32 v223, v126, v127
	s_setprio 0
	s_branch .LBB1_298
